# hand-written RMS-norm row loop (non-dual): all adaLN vector loads issued together, two 4-row batches of x in flight (software pipelined), DPP wave reduction instead of six LDS permute round trips, f32
# speedup vs baseline: 1.0018x; 1.0018x over previous
.LBB0_533:
	s_ashr_i32 s2, s24, 8
	v_mad_i64_i32 v[86:87], s[4:5], s2, v207, v[82:83]
	v_mad_i64_i32 v[88:89], s[4:5], s2, v207, v[80:81]
	global_load_dwordx4 v[100:103], v[86:87], off
	global_load_dwordx4 v[104:107], v[86:87], off offset:1024
	global_load_dwordx4 v[108:111], v[86:87], off offset:2048
	global_load_dwordx4 v[112:115], v[86:87], off offset:3072
	global_load_dwordx4 v[64:67], v[96:97], off
	global_load_dwordx4 v[68:71], v[96:97], off offset:1024
	global_load_dwordx4 v[72:75], v[96:97], off offset:2048
	global_load_dwordx4 v[76:79], v[96:97], off offset:3072
	global_load_dwordx4 v[116:119], v[88:89], off
	global_load_dwordx4 v[120:123], v[88:89], off offset:1024
	global_load_dwordx4 v[124:127], v[88:89], off offset:2048
	global_load_dwordx4 v[128:131], v[88:89], off offset:3072
	s_ashr_i32 s7, s6, 31
	s_lshl_b64 s[14:15], s[6:7], 12
	s_add_u32 s14, s30, s14
	s_addc_u32 s15, s31, s15
	s_lshl_b64 s[20:21], s[6:7], 11
	v_mov_b32_e32 v228, s70
	v_lshl_add_u64 v[230:231], s[14:15], 0, v[174:175]
	global_load_dwordx4 v[0:3], v[230:231], off
	global_load_dwordx4 v[4:7], v[230:231], off offset:1024
	global_load_dwordx4 v[8:11], v[230:231], off offset:2048
	global_load_dwordx4 v[12:15], v[230:231], off offset:3072
	s_add_u32 s14, s14, 0x1000
	s_addc_u32 s15, s15, 0
	v_lshl_add_u64 v[232:233], s[14:15], 0, v[174:175]
	global_load_dwordx4 v[16:19], v[232:233], off
	global_load_dwordx4 v[20:23], v[232:233], off offset:1024
	global_load_dwordx4 v[24:27], v[232:233], off offset:2048
	global_load_dwordx4 v[28:31], v[232:233], off offset:3072
	s_add_u32 s14, s14, 0x1000
	s_addc_u32 s15, s15, 0
	v_lshl_add_u64 v[230:231], s[14:15], 0, v[174:175]
	global_load_dwordx4 v[32:35], v[230:231], off
	global_load_dwordx4 v[36:39], v[230:231], off offset:1024
	global_load_dwordx4 v[40:43], v[230:231], off offset:2048
	global_load_dwordx4 v[44:47], v[230:231], off offset:3072
	s_add_u32 s14, s14, 0x1000
	s_addc_u32 s15, s15, 0
	v_lshl_add_u64 v[232:233], s[14:15], 0, v[174:175]
	global_load_dwordx4 v[48:51], v[232:233], off
	global_load_dwordx4 v[52:55], v[232:233], off offset:1024
	global_load_dwordx4 v[56:59], v[232:233], off offset:2048
	global_load_dwordx4 v[60:63], v[232:233], off offset:3072
	s_add_u32 s14, s14, 0x1000
	s_addc_u32 s15, s15, 0
	v_lshl_add_u64 v[230:231], s[14:15], 0, v[174:175]
	global_load_dwordx4 v[136:139], v[230:231], off
	global_load_dwordx4 v[140:143], v[230:231], off offset:1024
	global_load_dwordx4 v[144:147], v[230:231], off offset:2048
	global_load_dwordx4 v[148:151], v[230:231], off offset:3072
	s_add_u32 s14, s14, 0x1000
	s_addc_u32 s15, s15, 0
	v_lshl_add_u64 v[232:233], s[14:15], 0, v[174:175]
	global_load_dwordx4 v[152:155], v[232:233], off
	global_load_dwordx4 v[156:159], v[232:233], off offset:1024
	global_load_dwordx4 v[160:163], v[232:233], off offset:2048
	global_load_dwordx4 v[164:167], v[232:233], off offset:3072
	s_add_u32 s14, s14, 0x1000
	s_addc_u32 s15, s15, 0
	v_lshl_add_u64 v[230:231], s[14:15], 0, v[174:175]
	global_load_dwordx4 v[168:171], v[230:231], off
	global_load_dwordx4 v[184:187], v[230:231], off offset:1024
	global_load_dwordx4 v[188:191], v[230:231], off offset:2048
	global_load_dwordx4 v[192:195], v[230:231], off offset:3072
	s_add_u32 s14, s14, 0x1000
	s_addc_u32 s15, s15, 0
	v_lshl_add_u64 v[232:233], s[14:15], 0, v[174:175]
	global_load_dwordx4 v[196:199], v[232:233], off
	global_load_dwordx4 v[200:203], v[232:233], off offset:1024
	global_load_dwordx4 v[212:215], v[232:233], off offset:2048
	global_load_dwordx4 v[216:219], v[232:233], off offset:3072
	s_add_u32 s14, s14, 0x1000
	s_addc_u32 s15, s15, 0
	s_waitcnt vmcnt(32)
	v_pk_add_f32 v[100:101], v[100:101], 1.0 op_sel_hi:[1,0]
	v_pk_add_f32 v[102:103], v[102:103], 1.0 op_sel_hi:[1,0]
	v_pk_add_f32 v[104:105], v[104:105], 1.0 op_sel_hi:[1,0]
	v_pk_add_f32 v[106:107], v[106:107], 1.0 op_sel_hi:[1,0]
	v_pk_add_f32 v[108:109], v[108:109], 1.0 op_sel_hi:[1,0]
	v_pk_add_f32 v[110:111], v[110:111], 1.0 op_sel_hi:[1,0]
	v_pk_add_f32 v[112:113], v[112:113], 1.0 op_sel_hi:[1,0]
	v_pk_add_f32 v[114:115], v[114:115], 1.0 op_sel_hi:[1,0]
	v_pk_mul_f32 v[64:65], v[64:65], v[100:101]
	v_pk_mul_f32 v[66:67], v[66:67], v[102:103]
	v_pk_mul_f32 v[68:69], v[68:69], v[104:105]
	v_pk_mul_f32 v[70:71], v[70:71], v[106:107]
	v_pk_mul_f32 v[72:73], v[72:73], v[108:109]
	v_pk_mul_f32 v[74:75], v[74:75], v[110:111]
	v_pk_mul_f32 v[76:77], v[76:77], v[112:113]
	v_pk_mul_f32 v[78:79], v[78:79], v[114:115]
	s_waitcnt vmcnt(16)
	v_pk_mul_f32 v[220:221], v[0:1], v[0:1]
	v_pk_mul_f32 v[222:223], v[16:17], v[16:17]
	v_pk_mul_f32 v[224:225], v[32:33], v[32:33]
	v_pk_mul_f32 v[226:227], v[48:49], v[48:49]
	v_pk_fma_f32 v[220:221], v[2:3], v[2:3], v[220:221]
	v_pk_fma_f32 v[222:223], v[18:19], v[18:19], v[222:223]
	v_pk_fma_f32 v[224:225], v[34:35], v[34:35], v[224:225]
	v_pk_fma_f32 v[226:227], v[50:51], v[50:51], v[226:227]
	v_pk_fma_f32 v[220:221], v[4:5], v[4:5], v[220:221]
	v_pk_fma_f32 v[222:223], v[20:21], v[20:21], v[222:223]
	v_pk_fma_f32 v[224:225], v[36:37], v[36:37], v[224:225]
	v_pk_fma_f32 v[226:227], v[52:53], v[52:53], v[226:227]
	v_pk_fma_f32 v[220:221], v[6:7], v[6:7], v[220:221]
	v_pk_fma_f32 v[222:223], v[22:23], v[22:23], v[222:223]
	v_pk_fma_f32 v[224:225], v[38:39], v[38:39], v[224:225]
	v_pk_fma_f32 v[226:227], v[54:55], v[54:55], v[226:227]
	v_pk_fma_f32 v[220:221], v[8:9], v[8:9], v[220:221]
	v_pk_fma_f32 v[222:223], v[24:25], v[24:25], v[222:223]
	v_pk_fma_f32 v[224:225], v[40:41], v[40:41], v[224:225]
	v_pk_fma_f32 v[226:227], v[56:57], v[56:57], v[226:227]
	v_pk_fma_f32 v[220:221], v[10:11], v[10:11], v[220:221]
	v_pk_fma_f32 v[222:223], v[26:27], v[26:27], v[222:223]
	v_pk_fma_f32 v[224:225], v[42:43], v[42:43], v[224:225]
	v_pk_fma_f32 v[226:227], v[58:59], v[58:59], v[226:227]
	v_pk_fma_f32 v[220:221], v[12:13], v[12:13], v[220:221]
	v_pk_fma_f32 v[222:223], v[28:29], v[28:29], v[222:223]
	v_pk_fma_f32 v[224:225], v[44:45], v[44:45], v[224:225]
	v_pk_fma_f32 v[226:227], v[60:61], v[60:61], v[226:227]
	v_pk_fma_f32 v[220:221], v[14:15], v[14:15], v[220:221]
	v_pk_fma_f32 v[222:223], v[30:31], v[30:31], v[222:223]
	v_pk_fma_f32 v[224:225], v[46:47], v[46:47], v[224:225]
	v_pk_fma_f32 v[226:227], v[62:63], v[62:63], v[226:227]
	v_add_f32_e32 v220, v220, v221
	v_add_f32_e32 v222, v222, v223
	v_add_f32_e32 v224, v224, v225
	v_add_f32_e32 v226, v226, v227
	v_add_f32_dpp v220, v220, v220 quad_perm:[1,0,3,2] row_mask:0xf bank_mask:0xf
	v_add_f32_dpp v222, v222, v222 quad_perm:[1,0,3,2] row_mask:0xf bank_mask:0xf
	v_add_f32_dpp v224, v224, v224 quad_perm:[1,0,3,2] row_mask:0xf bank_mask:0xf
	v_add_f32_dpp v226, v226, v226 quad_perm:[1,0,3,2] row_mask:0xf bank_mask:0xf
	v_add_f32_dpp v220, v220, v220 quad_perm:[2,3,0,1] row_mask:0xf bank_mask:0xf
	v_add_f32_dpp v222, v222, v222 quad_perm:[2,3,0,1] row_mask:0xf bank_mask:0xf
	v_add_f32_dpp v224, v224, v224 quad_perm:[2,3,0,1] row_mask:0xf bank_mask:0xf
	v_add_f32_dpp v226, v226, v226 quad_perm:[2,3,0,1] row_mask:0xf bank_mask:0xf
	v_add_f32_dpp v220, v220, v220 row_half_mirror row_mask:0xf bank_mask:0xf
	v_add_f32_dpp v222, v222, v222 row_half_mirror row_mask:0xf bank_mask:0xf
	v_add_f32_dpp v224, v224, v224 row_half_mirror row_mask:0xf bank_mask:0xf
	v_add_f32_dpp v226, v226, v226 row_half_mirror row_mask:0xf bank_mask:0xf
	v_add_f32_dpp v220, v220, v220 row_mirror row_mask:0xf bank_mask:0xf
	v_add_f32_dpp v222, v222, v222 row_mirror row_mask:0xf bank_mask:0xf
	v_add_f32_dpp v224, v224, v224 row_mirror row_mask:0xf bank_mask:0xf
	v_add_f32_dpp v226, v226, v226 row_mirror row_mask:0xf bank_mask:0xf
	v_add_f32_dpp v220, v220, v220 row_bcast:15 row_mask:0xa bank_mask:0xf
	v_add_f32_dpp v222, v222, v222 row_bcast:15 row_mask:0xa bank_mask:0xf
	v_add_f32_dpp v224, v224, v224 row_bcast:15 row_mask:0xa bank_mask:0xf
	v_add_f32_dpp v226, v226, v226 row_bcast:15 row_mask:0xa bank_mask:0xf
	v_add_f32_dpp v220, v220, v220 row_bcast:31 row_mask:0xc bank_mask:0xf
	v_add_f32_dpp v222, v222, v222 row_bcast:31 row_mask:0xc bank_mask:0xf
	v_add_f32_dpp v224, v224, v224 row_bcast:31 row_mask:0xc bank_mask:0xf
	v_add_f32_dpp v226, v226, v226 row_bcast:31 row_mask:0xc bank_mask:0xf
	v_fma_f32 v220, v220, s88, v228
	v_fma_f32 v222, v222, s88, v228
	v_fma_f32 v224, v224, s88, v228
	v_fma_f32 v226, v226, s88, v228
	v_rsq_f32_e32 v220, v220
	v_rsq_f32_e32 v222, v222
	v_rsq_f32_e32 v224, v224
	v_rsq_f32_e32 v226, v226
	v_readlane_b32 s16, v220, 63
	v_readlane_b32 s17, v222, 63
	v_readlane_b32 s18, v224, 63
	v_readlane_b32 s19, v226, 63
	v_lshl_add_u64 v[230:231], v[84:85], 0, s[20:21]
	s_add_u32 s20, s20, 0x1000
	s_addc_u32 s21, s21, 0
	v_lshl_add_u64 v[232:233], v[84:85], 0, s[20:21]
	s_add_u32 s20, s20, 0x1000
	s_addc_u32 s21, s21, 0
	v_pk_mul_f32 v[0:1], v[0:1], s[16:17] op_sel_hi:[1,0]
	v_pk_mul_f32 v[2:3], v[2:3], s[16:17] op_sel_hi:[1,0]
	v_pk_mul_f32 v[4:5], v[4:5], s[16:17] op_sel_hi:[1,0]
	v_pk_mul_f32 v[6:7], v[6:7], s[16:17] op_sel_hi:[1,0]
	v_pk_mul_f32 v[8:9], v[8:9], s[16:17] op_sel_hi:[1,0]
	v_pk_mul_f32 v[10:11], v[10:11], s[16:17] op_sel_hi:[1,0]
	v_pk_mul_f32 v[12:13], v[12:13], s[16:17] op_sel_hi:[1,0]
	v_pk_mul_f32 v[14:15], v[14:15], s[16:17] op_sel_hi:[1,0]
	v_pk_mul_f32 v[16:17], v[16:17], s[16:17] op_sel:[0,1] op_sel_hi:[1,1]
	v_pk_mul_f32 v[18:19], v[18:19], s[16:17] op_sel:[0,1] op_sel_hi:[1,1]
	v_pk_mul_f32 v[20:21], v[20:21], s[16:17] op_sel:[0,1] op_sel_hi:[1,1]
	v_pk_mul_f32 v[22:23], v[22:23], s[16:17] op_sel:[0,1] op_sel_hi:[1,1]
	v_pk_mul_f32 v[24:25], v[24:25], s[16:17] op_sel:[0,1] op_sel_hi:[1,1]
	v_pk_mul_f32 v[26:27], v[26:27], s[16:17] op_sel:[0,1] op_sel_hi:[1,1]
	v_pk_mul_f32 v[28:29], v[28:29], s[16:17] op_sel:[0,1] op_sel_hi:[1,1]
	v_pk_mul_f32 v[30:31], v[30:31], s[16:17] op_sel:[0,1] op_sel_hi:[1,1]
	v_pk_mul_f32 v[32:33], v[32:33], s[18:19] op_sel_hi:[1,0]
	v_pk_mul_f32 v[34:35], v[34:35], s[18:19] op_sel_hi:[1,0]
	v_pk_mul_f32 v[36:37], v[36:37], s[18:19] op_sel_hi:[1,0]
	v_pk_mul_f32 v[38:39], v[38:39], s[18:19] op_sel_hi:[1,0]
	v_pk_mul_f32 v[40:41], v[40:41], s[18:19] op_sel_hi:[1,0]
	v_pk_mul_f32 v[42:43], v[42:43], s[18:19] op_sel_hi:[1,0]
	v_pk_mul_f32 v[44:45], v[44:45], s[18:19] op_sel_hi:[1,0]
	v_pk_mul_f32 v[46:47], v[46:47], s[18:19] op_sel_hi:[1,0]
	v_pk_mul_f32 v[48:49], v[48:49], s[18:19] op_sel:[0,1] op_sel_hi:[1,1]
	v_pk_mul_f32 v[50:51], v[50:51], s[18:19] op_sel:[0,1] op_sel_hi:[1,1]
	v_pk_mul_f32 v[52:53], v[52:53], s[18:19] op_sel:[0,1] op_sel_hi:[1,1]
	v_pk_mul_f32 v[54:55], v[54:55], s[18:19] op_sel:[0,1] op_sel_hi:[1,1]
	v_pk_mul_f32 v[56:57], v[56:57], s[18:19] op_sel:[0,1] op_sel_hi:[1,1]
	v_pk_mul_f32 v[58:59], v[58:59], s[18:19] op_sel:[0,1] op_sel_hi:[1,1]
	v_pk_mul_f32 v[60:61], v[60:61], s[18:19] op_sel:[0,1] op_sel_hi:[1,1]
	v_pk_mul_f32 v[62:63], v[62:63], s[18:19] op_sel:[0,1] op_sel_hi:[1,1]
	v_pk_fma_f32 v[0:1], v[64:65], v[0:1], v[116:117]
	v_pk_fma_f32 v[2:3], v[66:67], v[2:3], v[118:119]
	v_pk_fma_f32 v[4:5], v[68:69], v[4:5], v[120:121]
	v_pk_fma_f32 v[6:7], v[70:71], v[6:7], v[122:123]
	v_pk_fma_f32 v[8:9], v[72:73], v[8:9], v[124:125]
	v_pk_fma_f32 v[10:11], v[74:75], v[10:11], v[126:127]
	v_pk_fma_f32 v[12:13], v[76:77], v[12:13], v[128:129]
	v_pk_fma_f32 v[14:15], v[78:79], v[14:15], v[130:131]
	v_pk_fma_f32 v[16:17], v[64:65], v[16:17], v[116:117]
	v_pk_fma_f32 v[18:19], v[66:67], v[18:19], v[118:119]
	v_pk_fma_f32 v[20:21], v[68:69], v[20:21], v[120:121]
	v_pk_fma_f32 v[22:23], v[70:71], v[22:23], v[122:123]
	v_pk_fma_f32 v[24:25], v[72:73], v[24:25], v[124:125]
	v_pk_fma_f32 v[26:27], v[74:75], v[26:27], v[126:127]
	v_pk_fma_f32 v[28:29], v[76:77], v[28:29], v[128:129]
	v_pk_fma_f32 v[30:31], v[78:79], v[30:31], v[130:131]
	v_pk_fma_f32 v[32:33], v[64:65], v[32:33], v[116:117]
	v_pk_fma_f32 v[34:35], v[66:67], v[34:35], v[118:119]
	v_pk_fma_f32 v[36:37], v[68:69], v[36:37], v[120:121]
	v_pk_fma_f32 v[38:39], v[70:71], v[38:39], v[122:123]
	v_pk_fma_f32 v[40:41], v[72:73], v[40:41], v[124:125]
	v_pk_fma_f32 v[42:43], v[74:75], v[42:43], v[126:127]
	v_pk_fma_f32 v[44:45], v[76:77], v[44:45], v[128:129]
	v_pk_fma_f32 v[46:47], v[78:79], v[46:47], v[130:131]
	v_pk_fma_f32 v[48:49], v[64:65], v[48:49], v[116:117]
	v_pk_fma_f32 v[50:51], v[66:67], v[50:51], v[118:119]
	v_pk_fma_f32 v[52:53], v[68:69], v[52:53], v[120:121]
	v_pk_fma_f32 v[54:55], v[70:71], v[54:55], v[122:123]
	v_pk_fma_f32 v[56:57], v[72:73], v[56:57], v[124:125]
	v_pk_fma_f32 v[58:59], v[74:75], v[58:59], v[126:127]
	v_pk_fma_f32 v[60:61], v[76:77], v[60:61], v[128:129]
	v_pk_fma_f32 v[62:63], v[78:79], v[62:63], v[130:131]
	v_cvt_pk_bf16_f32 v0, v0, v1
	v_cvt_pk_bf16_f32 v1, v2, v3
	v_cvt_pk_bf16_f32 v4, v4, v5
	v_cvt_pk_bf16_f32 v5, v6, v7
	v_cvt_pk_bf16_f32 v8, v8, v9
	v_cvt_pk_bf16_f32 v9, v10, v11
	v_cvt_pk_bf16_f32 v12, v12, v13
	v_cvt_pk_bf16_f32 v13, v14, v15
	v_cvt_pk_bf16_f32 v16, v16, v17
	v_cvt_pk_bf16_f32 v17, v18, v19
	v_cvt_pk_bf16_f32 v20, v20, v21
	v_cvt_pk_bf16_f32 v21, v22, v23
	v_cvt_pk_bf16_f32 v24, v24, v25
	v_cvt_pk_bf16_f32 v25, v26, v27
	v_cvt_pk_bf16_f32 v28, v28, v29
	v_cvt_pk_bf16_f32 v29, v30, v31
	v_cvt_pk_bf16_f32 v32, v32, v33
	v_cvt_pk_bf16_f32 v33, v34, v35
	v_cvt_pk_bf16_f32 v36, v36, v37
	v_cvt_pk_bf16_f32 v37, v38, v39
	v_cvt_pk_bf16_f32 v40, v40, v41
	v_cvt_pk_bf16_f32 v41, v42, v43
	v_cvt_pk_bf16_f32 v44, v44, v45
	v_cvt_pk_bf16_f32 v45, v46, v47
	v_cvt_pk_bf16_f32 v48, v48, v49
	v_cvt_pk_bf16_f32 v49, v50, v51
	v_cvt_pk_bf16_f32 v52, v52, v53
	v_cvt_pk_bf16_f32 v53, v54, v55
	v_cvt_pk_bf16_f32 v56, v56, v57
	v_cvt_pk_bf16_f32 v57, v58, v59
	v_cvt_pk_bf16_f32 v60, v60, v61
	v_cvt_pk_bf16_f32 v61, v62, v63
	global_store_dwordx2 v[230:231], v[0:1], off
	global_store_dwordx2 v[230:231], v[4:5], off offset:512
	global_store_dwordx2 v[230:231], v[8:9], off offset:1024
	global_store_dwordx2 v[230:231], v[12:13], off offset:1536
	global_store_dwordx2 v[230:231], v[16:17], off offset:2048
	global_store_dwordx2 v[230:231], v[20:21], off offset:2560
	global_store_dwordx2 v[230:231], v[24:25], off offset:3072
	global_store_dwordx2 v[230:231], v[28:29], off offset:3584
	global_store_dwordx2 v[232:233], v[32:33], off
	global_store_dwordx2 v[232:233], v[36:37], off offset:512
	global_store_dwordx2 v[232:233], v[40:41], off offset:1024
	global_store_dwordx2 v[232:233], v[44:45], off offset:1536
	global_store_dwordx2 v[232:233], v[48:49], off offset:2048
	global_store_dwordx2 v[232:233], v[52:53], off offset:2560
	global_store_dwordx2 v[232:233], v[56:57], off offset:3072
	global_store_dwordx2 v[232:233], v[60:61], off offset:3584
	v_lshl_add_u64 v[230:231], s[14:15], 0, v[174:175]
	global_load_dwordx4 v[0:3], v[230:231], off
	global_load_dwordx4 v[4:7], v[230:231], off offset:1024
	global_load_dwordx4 v[8:11], v[230:231], off offset:2048
	global_load_dwordx4 v[12:15], v[230:231], off offset:3072
	s_add_u32 s14, s14, 0x1000
	s_addc_u32 s15, s15, 0
	v_lshl_add_u64 v[232:233], s[14:15], 0, v[174:175]
	global_load_dwordx4 v[16:19], v[232:233], off
	global_load_dwordx4 v[20:23], v[232:233], off offset:1024
	global_load_dwordx4 v[24:27], v[232:233], off offset:2048
	global_load_dwordx4 v[28:31], v[232:233], off offset:3072
	s_add_u32 s14, s14, 0x1000
	s_addc_u32 s15, s15, 0
	v_lshl_add_u64 v[230:231], s[14:15], 0, v[174:175]
	global_load_dwordx4 v[32:35], v[230:231], off
	global_load_dwordx4 v[36:39], v[230:231], off offset:1024
	global_load_dwordx4 v[40:43], v[230:231], off offset:2048
	global_load_dwordx4 v[44:47], v[230:231], off offset:3072
	s_add_u32 s14, s14, 0x1000
	s_addc_u32 s15, s15, 0
	v_lshl_add_u64 v[232:233], s[14:15], 0, v[174:175]
	global_load_dwordx4 v[48:51], v[232:233], off
	global_load_dwordx4 v[52:55], v[232:233], off offset:1024
	global_load_dwordx4 v[56:59], v[232:233], off offset:2048
	global_load_dwordx4 v[60:63], v[232:233], off offset:3072
	s_add_u32 s14, s14, 0x1000
	s_addc_u32 s15, s15, 0
	s_waitcnt vmcnt(32)
	v_pk_mul_f32 v[220:221], v[136:137], v[136:137]
	v_pk_mul_f32 v[222:223], v[152:153], v[152:153]
	v_pk_mul_f32 v[224:225], v[168:169], v[168:169]
	v_pk_mul_f32 v[226:227], v[196:197], v[196:197]
	v_pk_fma_f32 v[220:221], v[138:139], v[138:139], v[220:221]
	v_pk_fma_f32 v[222:223], v[154:155], v[154:155], v[222:223]
	v_pk_fma_f32 v[224:225], v[170:171], v[170:171], v[224:225]
	v_pk_fma_f32 v[226:227], v[198:199], v[198:199], v[226:227]
	v_pk_fma_f32 v[220:221], v[140:141], v[140:141], v[220:221]
	v_pk_fma_f32 v[222:223], v[156:157], v[156:157], v[222:223]
	v_pk_fma_f32 v[224:225], v[184:185], v[184:185], v[224:225]
	v_pk_fma_f32 v[226:227], v[200:201], v[200:201], v[226:227]
	v_pk_fma_f32 v[220:221], v[142:143], v[142:143], v[220:221]
	v_pk_fma_f32 v[222:223], v[158:159], v[158:159], v[222:223]
	v_pk_fma_f32 v[224:225], v[186:187], v[186:187], v[224:225]
	v_pk_fma_f32 v[226:227], v[202:203], v[202:203], v[226:227]
	v_pk_fma_f32 v[220:221], v[144:145], v[144:145], v[220:221]
	v_pk_fma_f32 v[222:223], v[160:161], v[160:161], v[222:223]
	v_pk_fma_f32 v[224:225], v[188:189], v[188:189], v[224:225]
	v_pk_fma_f32 v[226:227], v[212:213], v[212:213], v[226:227]
	v_pk_fma_f32 v[220:221], v[146:147], v[146:147], v[220:221]
	v_pk_fma_f32 v[222:223], v[162:163], v[162:163], v[222:223]
	v_pk_fma_f32 v[224:225], v[190:191], v[190:191], v[224:225]
	v_pk_fma_f32 v[226:227], v[214:215], v[214:215], v[226:227]
	v_pk_fma_f32 v[220:221], v[148:149], v[148:149], v[220:221]
	v_pk_fma_f32 v[222:223], v[164:165], v[164:165], v[222:223]
	v_pk_fma_f32 v[224:225], v[192:193], v[192:193], v[224:225]
	v_pk_fma_f32 v[226:227], v[216:217], v[216:217], v[226:227]
	v_pk_fma_f32 v[220:221], v[150:151], v[150:151], v[220:221]
	v_pk_fma_f32 v[222:223], v[166:167], v[166:167], v[222:223]
	v_pk_fma_f32 v[224:225], v[194:195], v[194:195], v[224:225]
	v_pk_fma_f32 v[226:227], v[218:219], v[218:219], v[226:227]
	v_add_f32_e32 v220, v220, v221
	v_add_f32_e32 v222, v222, v223
	v_add_f32_e32 v224, v224, v225
	v_add_f32_e32 v226, v226, v227
	v_add_f32_dpp v220, v220, v220 quad_perm:[1,0,3,2] row_mask:0xf bank_mask:0xf
	v_add_f32_dpp v222, v222, v222 quad_perm:[1,0,3,2] row_mask:0xf bank_mask:0xf
	v_add_f32_dpp v224, v224, v224 quad_perm:[1,0,3,2] row_mask:0xf bank_mask:0xf
	v_add_f32_dpp v226, v226, v226 quad_perm:[1,0,3,2] row_mask:0xf bank_mask:0xf
	v_add_f32_dpp v220, v220, v220 quad_perm:[2,3,0,1] row_mask:0xf bank_mask:0xf
	v_add_f32_dpp v222, v222, v222 quad_perm:[2,3,0,1] row_mask:0xf bank_mask:0xf
	v_add_f32_dpp v224, v224, v224 quad_perm:[2,3,0,1] row_mask:0xf bank_mask:0xf
	v_add_f32_dpp v226, v226, v226 quad_perm:[2,3,0,1] row_mask:0xf bank_mask:0xf
	v_add_f32_dpp v220, v220, v220 row_half_mirror row_mask:0xf bank_mask:0xf
	v_add_f32_dpp v222, v222, v222 row_half_mirror row_mask:0xf bank_mask:0xf
	v_add_f32_dpp v224, v224, v224 row_half_mirror row_mask:0xf bank_mask:0xf
	v_add_f32_dpp v226, v226, v226 row_half_mirror row_mask:0xf bank_mask:0xf
	v_add_f32_dpp v220, v220, v220 row_mirror row_mask:0xf bank_mask:0xf
	v_add_f32_dpp v222, v222, v222 row_mirror row_mask:0xf bank_mask:0xf
	v_add_f32_dpp v224, v224, v224 row_mirror row_mask:0xf bank_mask:0xf
	v_add_f32_dpp v226, v226, v226 row_mirror row_mask:0xf bank_mask:0xf
	v_add_f32_dpp v220, v220, v220 row_bcast:15 row_mask:0xa bank_mask:0xf
	v_add_f32_dpp v222, v222, v222 row_bcast:15 row_mask:0xa bank_mask:0xf
	v_add_f32_dpp v224, v224, v224 row_bcast:15 row_mask:0xa bank_mask:0xf
	v_add_f32_dpp v226, v226, v226 row_bcast:15 row_mask:0xa bank_mask:0xf
	v_add_f32_dpp v220, v220, v220 row_bcast:31 row_mask:0xc bank_mask:0xf
	v_add_f32_dpp v222, v222, v222 row_bcast:31 row_mask:0xc bank_mask:0xf
	v_add_f32_dpp v224, v224, v224 row_bcast:31 row_mask:0xc bank_mask:0xf
	v_add_f32_dpp v226, v226, v226 row_bcast:31 row_mask:0xc bank_mask:0xf
	v_fma_f32 v220, v220, s88, v228
	v_fma_f32 v222, v222, s88, v228
	v_fma_f32 v224, v224, s88, v228
	v_fma_f32 v226, v226, s88, v228
	v_rsq_f32_e32 v220, v220
	v_rsq_f32_e32 v222, v222
	v_rsq_f32_e32 v224, v224
	v_rsq_f32_e32 v226, v226
	v_readlane_b32 s16, v220, 63
	v_readlane_b32 s17, v222, 63
	v_readlane_b32 s18, v224, 63
	v_readlane_b32 s19, v226, 63
	v_lshl_add_u64 v[230:231], v[84:85], 0, s[20:21]
	s_add_u32 s20, s20, 0x1000
	s_addc_u32 s21, s21, 0
	v_lshl_add_u64 v[232:233], v[84:85], 0, s[20:21]
	s_add_u32 s20, s20, 0x1000
	s_addc_u32 s21, s21, 0
	v_pk_mul_f32 v[136:137], v[136:137], s[16:17] op_sel_hi:[1,0]
	v_pk_mul_f32 v[138:139], v[138:139], s[16:17] op_sel_hi:[1,0]
	v_pk_mul_f32 v[140:141], v[140:141], s[16:17] op_sel_hi:[1,0]
	v_pk_mul_f32 v[142:143], v[142:143], s[16:17] op_sel_hi:[1,0]
	v_pk_mul_f32 v[144:145], v[144:145], s[16:17] op_sel_hi:[1,0]
	v_pk_mul_f32 v[146:147], v[146:147], s[16:17] op_sel_hi:[1,0]
	v_pk_mul_f32 v[148:149], v[148:149], s[16:17] op_sel_hi:[1,0]
	v_pk_mul_f32 v[150:151], v[150:151], s[16:17] op_sel_hi:[1,0]
	v_pk_mul_f32 v[152:153], v[152:153], s[16:17] op_sel:[0,1] op_sel_hi:[1,1]
	v_pk_mul_f32 v[154:155], v[154:155], s[16:17] op_sel:[0,1] op_sel_hi:[1,1]
	v_pk_mul_f32 v[156:157], v[156:157], s[16:17] op_sel:[0,1] op_sel_hi:[1,1]
	v_pk_mul_f32 v[158:159], v[158:159], s[16:17] op_sel:[0,1] op_sel_hi:[1,1]
	v_pk_mul_f32 v[160:161], v[160:161], s[16:17] op_sel:[0,1] op_sel_hi:[1,1]
	v_pk_mul_f32 v[162:163], v[162:163], s[16:17] op_sel:[0,1] op_sel_hi:[1,1]
	v_pk_mul_f32 v[164:165], v[164:165], s[16:17] op_sel:[0,1] op_sel_hi:[1,1]
	v_pk_mul_f32 v[166:167], v[166:167], s[16:17] op_sel:[0,1] op_sel_hi:[1,1]
	v_pk_mul_f32 v[168:169], v[168:169], s[18:19] op_sel_hi:[1,0]
	v_pk_mul_f32 v[170:171], v[170:171], s[18:19] op_sel_hi:[1,0]
	v_pk_mul_f32 v[184:185], v[184:185], s[18:19] op_sel_hi:[1,0]
	v_pk_mul_f32 v[186:187], v[186:187], s[18:19] op_sel_hi:[1,0]
	v_pk_mul_f32 v[188:189], v[188:189], s[18:19] op_sel_hi:[1,0]
	v_pk_mul_f32 v[190:191], v[190:191], s[18:19] op_sel_hi:[1,0]
	v_pk_mul_f32 v[192:193], v[192:193], s[18:19] op_sel_hi:[1,0]
	v_pk_mul_f32 v[194:195], v[194:195], s[18:19] op_sel_hi:[1,0]
	v_pk_mul_f32 v[196:197], v[196:197], s[18:19] op_sel:[0,1] op_sel_hi:[1,1]
	v_pk_mul_f32 v[198:199], v[198:199], s[18:19] op_sel:[0,1] op_sel_hi:[1,1]
	v_pk_mul_f32 v[200:201], v[200:201], s[18:19] op_sel:[0,1] op_sel_hi:[1,1]
	v_pk_mul_f32 v[202:203], v[202:203], s[18:19] op_sel:[0,1] op_sel_hi:[1,1]
	v_pk_mul_f32 v[212:213], v[212:213], s[18:19] op_sel:[0,1] op_sel_hi:[1,1]
	v_pk_mul_f32 v[214:215], v[214:215], s[18:19] op_sel:[0,1] op_sel_hi:[1,1]
	v_pk_mul_f32 v[216:217], v[216:217], s[18:19] op_sel:[0,1] op_sel_hi:[1,1]
	v_pk_mul_f32 v[218:219], v[218:219], s[18:19] op_sel:[0,1] op_sel_hi:[1,1]
	v_pk_fma_f32 v[136:137], v[64:65], v[136:137], v[116:117]
	v_pk_fma_f32 v[138:139], v[66:67], v[138:139], v[118:119]
	v_pk_fma_f32 v[140:141], v[68:69], v[140:141], v[120:121]
	v_pk_fma_f32 v[142:143], v[70:71], v[142:143], v[122:123]
	v_pk_fma_f32 v[144:145], v[72:73], v[144:145], v[124:125]
	v_pk_fma_f32 v[146:147], v[74:75], v[146:147], v[126:127]
	v_pk_fma_f32 v[148:149], v[76:77], v[148:149], v[128:129]
	v_pk_fma_f32 v[150:151], v[78:79], v[150:151], v[130:131]
	v_pk_fma_f32 v[152:153], v[64:65], v[152:153], v[116:117]
	v_pk_fma_f32 v[154:155], v[66:67], v[154:155], v[118:119]
	v_pk_fma_f32 v[156:157], v[68:69], v[156:157], v[120:121]
	v_pk_fma_f32 v[158:159], v[70:71], v[158:159], v[122:123]
	v_pk_fma_f32 v[160:161], v[72:73], v[160:161], v[124:125]
	v_pk_fma_f32 v[162:163], v[74:75], v[162:163], v[126:127]
	v_pk_fma_f32 v[164:165], v[76:77], v[164:165], v[128:129]
	v_pk_fma_f32 v[166:167], v[78:79], v[166:167], v[130:131]
	v_pk_fma_f32 v[168:169], v[64:65], v[168:169], v[116:117]
	v_pk_fma_f32 v[170:171], v[66:67], v[170:171], v[118:119]
	v_pk_fma_f32 v[184:185], v[68:69], v[184:185], v[120:121]
	v_pk_fma_f32 v[186:187], v[70:71], v[186:187], v[122:123]
	v_pk_fma_f32 v[188:189], v[72:73], v[188:189], v[124:125]
	v_pk_fma_f32 v[190:191], v[74:75], v[190:191], v[126:127]
	v_pk_fma_f32 v[192:193], v[76:77], v[192:193], v[128:129]
	v_pk_fma_f32 v[194:195], v[78:79], v[194:195], v[130:131]
	v_pk_fma_f32 v[196:197], v[64:65], v[196:197], v[116:117]
	v_pk_fma_f32 v[198:199], v[66:67], v[198:199], v[118:119]
	v_pk_fma_f32 v[200:201], v[68:69], v[200:201], v[120:121]
	v_pk_fma_f32 v[202:203], v[70:71], v[202:203], v[122:123]
	v_pk_fma_f32 v[212:213], v[72:73], v[212:213], v[124:125]
	v_pk_fma_f32 v[214:215], v[74:75], v[214:215], v[126:127]
	v_pk_fma_f32 v[216:217], v[76:77], v[216:217], v[128:129]
	v_pk_fma_f32 v[218:219], v[78:79], v[218:219], v[130:131]
	v_cvt_pk_bf16_f32 v136, v136, v137
	v_cvt_pk_bf16_f32 v137, v138, v139
	v_cvt_pk_bf16_f32 v140, v140, v141
	v_cvt_pk_bf16_f32 v141, v142, v143
	v_cvt_pk_bf16_f32 v144, v144, v145
	v_cvt_pk_bf16_f32 v145, v146, v147
	v_cvt_pk_bf16_f32 v148, v148, v149
	v_cvt_pk_bf16_f32 v149, v150, v151
	v_cvt_pk_bf16_f32 v152, v152, v153
	v_cvt_pk_bf16_f32 v153, v154, v155
	v_cvt_pk_bf16_f32 v156, v156, v157
	v_cvt_pk_bf16_f32 v157, v158, v159
	v_cvt_pk_bf16_f32 v160, v160, v161
	v_cvt_pk_bf16_f32 v161, v162, v163
	v_cvt_pk_bf16_f32 v164, v164, v165
	v_cvt_pk_bf16_f32 v165, v166, v167
	v_cvt_pk_bf16_f32 v168, v168, v169
	v_cvt_pk_bf16_f32 v169, v170, v171
	v_cvt_pk_bf16_f32 v184, v184, v185
	v_cvt_pk_bf16_f32 v185, v186, v187
	v_cvt_pk_bf16_f32 v188, v188, v189
	v_cvt_pk_bf16_f32 v189, v190, v191
	v_cvt_pk_bf16_f32 v192, v192, v193
	v_cvt_pk_bf16_f32 v193, v194, v195
	v_cvt_pk_bf16_f32 v196, v196, v197
	v_cvt_pk_bf16_f32 v197, v198, v199
	v_cvt_pk_bf16_f32 v200, v200, v201
	v_cvt_pk_bf16_f32 v201, v202, v203
	v_cvt_pk_bf16_f32 v212, v212, v213
	v_cvt_pk_bf16_f32 v213, v214, v215
	v_cvt_pk_bf16_f32 v216, v216, v217
	v_cvt_pk_bf16_f32 v217, v218, v219
	global_store_dwordx2 v[230:231], v[136:137], off
	global_store_dwordx2 v[230:231], v[140:141], off offset:512
	global_store_dwordx2 v[230:231], v[144:145], off offset:1024
	global_store_dwordx2 v[230:231], v[148:149], off offset:1536
	global_store_dwordx2 v[230:231], v[152:153], off offset:2048
	global_store_dwordx2 v[230:231], v[156:157], off offset:2560
	global_store_dwordx2 v[230:231], v[160:161], off offset:3072
	global_store_dwordx2 v[230:231], v[164:165], off offset:3584
	global_store_dwordx2 v[232:233], v[168:169], off
	global_store_dwordx2 v[232:233], v[184:185], off offset:512
	global_store_dwordx2 v[232:233], v[188:189], off offset:1024
	global_store_dwordx2 v[232:233], v[192:193], off offset:1536
	global_store_dwordx2 v[232:233], v[196:197], off offset:2048
	global_store_dwordx2 v[232:233], v[200:201], off offset:2560
	global_store_dwordx2 v[232:233], v[212:213], off offset:3072
	global_store_dwordx2 v[232:233], v[216:217], off offset:3584
	v_lshl_add_u64 v[230:231], s[14:15], 0, v[174:175]
	global_load_dwordx4 v[136:139], v[230:231], off
	global_load_dwordx4 v[140:143], v[230:231], off offset:1024
	global_load_dwordx4 v[144:147], v[230:231], off offset:2048
	global_load_dwordx4 v[148:151], v[230:231], off offset:3072
	s_add_u32 s14, s14, 0x1000
	s_addc_u32 s15, s15, 0
	v_lshl_add_u64 v[232:233], s[14:15], 0, v[174:175]
	global_load_dwordx4 v[152:155], v[232:233], off
	global_load_dwordx4 v[156:159], v[232:233], off offset:1024
	global_load_dwordx4 v[160:163], v[232:233], off offset:2048
	global_load_dwordx4 v[164:167], v[232:233], off offset:3072
	s_add_u32 s14, s14, 0x1000
	s_addc_u32 s15, s15, 0
	v_lshl_add_u64 v[230:231], s[14:15], 0, v[174:175]
	global_load_dwordx4 v[168:171], v[230:231], off
	global_load_dwordx4 v[184:187], v[230:231], off offset:1024
	global_load_dwordx4 v[188:191], v[230:231], off offset:2048
	global_load_dwordx4 v[192:195], v[230:231], off offset:3072
	s_add_u32 s14, s14, 0x1000
	s_addc_u32 s15, s15, 0
	v_lshl_add_u64 v[232:233], s[14:15], 0, v[174:175]
	global_load_dwordx4 v[196:199], v[232:233], off
	global_load_dwordx4 v[200:203], v[232:233], off offset:1024
	global_load_dwordx4 v[212:215], v[232:233], off offset:2048
	global_load_dwordx4 v[216:219], v[232:233], off offset:3072
	s_add_u32 s14, s14, 0x1000
	s_addc_u32 s15, s15, 0
	s_waitcnt vmcnt(32)
	v_pk_mul_f32 v[220:221], v[0:1], v[0:1]
	v_pk_mul_f32 v[222:223], v[16:17], v[16:17]
	v_pk_mul_f32 v[224:225], v[32:33], v[32:33]
	v_pk_mul_f32 v[226:227], v[48:49], v[48:49]
	v_pk_fma_f32 v[220:221], v[2:3], v[2:3], v[220:221]
	v_pk_fma_f32 v[222:223], v[18:19], v[18:19], v[222:223]
	v_pk_fma_f32 v[224:225], v[34:35], v[34:35], v[224:225]
	v_pk_fma_f32 v[226:227], v[50:51], v[50:51], v[226:227]
	v_pk_fma_f32 v[220:221], v[4:5], v[4:5], v[220:221]
	v_pk_fma_f32 v[222:223], v[20:21], v[20:21], v[222:223]
	v_pk_fma_f32 v[224:225], v[36:37], v[36:37], v[224:225]
	v_pk_fma_f32 v[226:227], v[52:53], v[52:53], v[226:227]
	v_pk_fma_f32 v[220:221], v[6:7], v[6:7], v[220:221]
	v_pk_fma_f32 v[222:223], v[22:23], v[22:23], v[222:223]
	v_pk_fma_f32 v[224:225], v[38:39], v[38:39], v[224:225]
	v_pk_fma_f32 v[226:227], v[54:55], v[54:55], v[226:227]
	v_pk_fma_f32 v[220:221], v[8:9], v[8:9], v[220:221]
	v_pk_fma_f32 v[222:223], v[24:25], v[24:25], v[222:223]
	v_pk_fma_f32 v[224:225], v[40:41], v[40:41], v[224:225]
	v_pk_fma_f32 v[226:227], v[56:57], v[56:57], v[226:227]
	v_pk_fma_f32 v[220:221], v[10:11], v[10:11], v[220:221]
	v_pk_fma_f32 v[222:223], v[26:27], v[26:27], v[222:223]
	v_pk_fma_f32 v[224:225], v[42:43], v[42:43], v[224:225]
	v_pk_fma_f32 v[226:227], v[58:59], v[58:59], v[226:227]
	v_pk_fma_f32 v[220:221], v[12:13], v[12:13], v[220:221]
	v_pk_fma_f32 v[222:223], v[28:29], v[28:29], v[222:223]
	v_pk_fma_f32 v[224:225], v[44:45], v[44:45], v[224:225]
	v_pk_fma_f32 v[226:227], v[60:61], v[60:61], v[226:227]
	v_pk_fma_f32 v[220:221], v[14:15], v[14:15], v[220:221]
	v_pk_fma_f32 v[222:223], v[30:31], v[30:31], v[222:223]
	v_pk_fma_f32 v[224:225], v[46:47], v[46:47], v[224:225]
	v_pk_fma_f32 v[226:227], v[62:63], v[62:63], v[226:227]
	v_add_f32_e32 v220, v220, v221
	v_add_f32_e32 v222, v222, v223
	v_add_f32_e32 v224, v224, v225
	v_add_f32_e32 v226, v226, v227
	v_add_f32_dpp v220, v220, v220 quad_perm:[1,0,3,2] row_mask:0xf bank_mask:0xf
	v_add_f32_dpp v222, v222, v222 quad_perm:[1,0,3,2] row_mask:0xf bank_mask:0xf
	v_add_f32_dpp v224, v224, v224 quad_perm:[1,0,3,2] row_mask:0xf bank_mask:0xf
	v_add_f32_dpp v226, v226, v226 quad_perm:[1,0,3,2] row_mask:0xf bank_mask:0xf
	v_add_f32_dpp v220, v220, v220 quad_perm:[2,3,0,1] row_mask:0xf bank_mask:0xf
	v_add_f32_dpp v222, v222, v222 quad_perm:[2,3,0,1] row_mask:0xf bank_mask:0xf
	v_add_f32_dpp v224, v224, v224 quad_perm:[2,3,0,1] row_mask:0xf bank_mask:0xf
	v_add_f32_dpp v226, v226, v226 quad_perm:[2,3,0,1] row_mask:0xf bank_mask:0xf
	v_add_f32_dpp v220, v220, v220 row_half_mirror row_mask:0xf bank_mask:0xf
	v_add_f32_dpp v222, v222, v222 row_half_mirror row_mask:0xf bank_mask:0xf
	v_add_f32_dpp v224, v224, v224 row_half_mirror row_mask:0xf bank_mask:0xf
	v_add_f32_dpp v226, v226, v226 row_half_mirror row_mask:0xf bank_mask:0xf
	v_add_f32_dpp v220, v220, v220 row_mirror row_mask:0xf bank_mask:0xf
	v_add_f32_dpp v222, v222, v222 row_mirror row_mask:0xf bank_mask:0xf
	v_add_f32_dpp v224, v224, v224 row_mirror row_mask:0xf bank_mask:0xf
	v_add_f32_dpp v226, v226, v226 row_mirror row_mask:0xf bank_mask:0xf
	v_add_f32_dpp v220, v220, v220 row_bcast:15 row_mask:0xa bank_mask:0xf
	v_add_f32_dpp v222, v222, v222 row_bcast:15 row_mask:0xa bank_mask:0xf
	v_add_f32_dpp v224, v224, v224 row_bcast:15 row_mask:0xa bank_mask:0xf
	v_add_f32_dpp v226, v226, v226 row_bcast:15 row_mask:0xa bank_mask:0xf
	v_add_f32_dpp v220, v220, v220 row_bcast:31 row_mask:0xc bank_mask:0xf
	v_add_f32_dpp v222, v222, v222 row_bcast:31 row_mask:0xc bank_mask:0xf
	v_add_f32_dpp v224, v224, v224 row_bcast:31 row_mask:0xc bank_mask:0xf
	v_add_f32_dpp v226, v226, v226 row_bcast:31 row_mask:0xc bank_mask:0xf
	v_fma_f32 v220, v220, s88, v228
	v_fma_f32 v222, v222, s88, v228
	v_fma_f32 v224, v224, s88, v228
	v_fma_f32 v226, v226, s88, v228
	v_rsq_f32_e32 v220, v220
	v_rsq_f32_e32 v222, v222
	v_rsq_f32_e32 v224, v224
	v_rsq_f32_e32 v226, v226
	v_readlane_b32 s16, v220, 63
	v_readlane_b32 s17, v222, 63
	v_readlane_b32 s18, v224, 63
	v_readlane_b32 s19, v226, 63
	v_lshl_add_u64 v[230:231], v[84:85], 0, s[20:21]
	s_add_u32 s20, s20, 0x1000
	s_addc_u32 s21, s21, 0
	v_lshl_add_u64 v[232:233], v[84:85], 0, s[20:21]
	s_add_u32 s20, s20, 0x1000
	s_addc_u32 s21, s21, 0
	v_pk_mul_f32 v[0:1], v[0:1], s[16:17] op_sel_hi:[1,0]
	v_pk_mul_f32 v[2:3], v[2:3], s[16:17] op_sel_hi:[1,0]
	v_pk_mul_f32 v[4:5], v[4:5], s[16:17] op_sel_hi:[1,0]
	v_pk_mul_f32 v[6:7], v[6:7], s[16:17] op_sel_hi:[1,0]
	v_pk_mul_f32 v[8:9], v[8:9], s[16:17] op_sel_hi:[1,0]
	v_pk_mul_f32 v[10:11], v[10:11], s[16:17] op_sel_hi:[1,0]
	v_pk_mul_f32 v[12:13], v[12:13], s[16:17] op_sel_hi:[1,0]
	v_pk_mul_f32 v[14:15], v[14:15], s[16:17] op_sel_hi:[1,0]
	v_pk_mul_f32 v[16:17], v[16:17], s[16:17] op_sel:[0,1] op_sel_hi:[1,1]
	v_pk_mul_f32 v[18:19], v[18:19], s[16:17] op_sel:[0,1] op_sel_hi:[1,1]
	v_pk_mul_f32 v[20:21], v[20:21], s[16:17] op_sel:[0,1] op_sel_hi:[1,1]
	v_pk_mul_f32 v[22:23], v[22:23], s[16:17] op_sel:[0,1] op_sel_hi:[1,1]
	v_pk_mul_f32 v[24:25], v[24:25], s[16:17] op_sel:[0,1] op_sel_hi:[1,1]
	v_pk_mul_f32 v[26:27], v[26:27], s[16:17] op_sel:[0,1] op_sel_hi:[1,1]
	v_pk_mul_f32 v[28:29], v[28:29], s[16:17] op_sel:[0,1] op_sel_hi:[1,1]
	v_pk_mul_f32 v[30:31], v[30:31], s[16:17] op_sel:[0,1] op_sel_hi:[1,1]
	v_pk_mul_f32 v[32:33], v[32:33], s[18:19] op_sel_hi:[1,0]
	v_pk_mul_f32 v[34:35], v[34:35], s[18:19] op_sel_hi:[1,0]
	v_pk_mul_f32 v[36:37], v[36:37], s[18:19] op_sel_hi:[1,0]
	v_pk_mul_f32 v[38:39], v[38:39], s[18:19] op_sel_hi:[1,0]
	v_pk_mul_f32 v[40:41], v[40:41], s[18:19] op_sel_hi:[1,0]
	v_pk_mul_f32 v[42:43], v[42:43], s[18:19] op_sel_hi:[1,0]
	v_pk_mul_f32 v[44:45], v[44:45], s[18:19] op_sel_hi:[1,0]
	v_pk_mul_f32 v[46:47], v[46:47], s[18:19] op_sel_hi:[1,0]
	v_pk_mul_f32 v[48:49], v[48:49], s[18:19] op_sel:[0,1] op_sel_hi:[1,1]
	v_pk_mul_f32 v[50:51], v[50:51], s[18:19] op_sel:[0,1] op_sel_hi:[1,1]
	v_pk_mul_f32 v[52:53], v[52:53], s[18:19] op_sel:[0,1] op_sel_hi:[1,1]
	v_pk_mul_f32 v[54:55], v[54:55], s[18:19] op_sel:[0,1] op_sel_hi:[1,1]
	v_pk_mul_f32 v[56:57], v[56:57], s[18:19] op_sel:[0,1] op_sel_hi:[1,1]
	v_pk_mul_f32 v[58:59], v[58:59], s[18:19] op_sel:[0,1] op_sel_hi:[1,1]
	v_pk_mul_f32 v[60:61], v[60:61], s[18:19] op_sel:[0,1] op_sel_hi:[1,1]
	v_pk_mul_f32 v[62:63], v[62:63], s[18:19] op_sel:[0,1] op_sel_hi:[1,1]
	v_pk_fma_f32 v[0:1], v[64:65], v[0:1], v[116:117]
	v_pk_fma_f32 v[2:3], v[66:67], v[2:3], v[118:119]
	v_pk_fma_f32 v[4:5], v[68:69], v[4:5], v[120:121]
	v_pk_fma_f32 v[6:7], v[70:71], v[6:7], v[122:123]
	v_pk_fma_f32 v[8:9], v[72:73], v[8:9], v[124:125]
	v_pk_fma_f32 v[10:11], v[74:75], v[10:11], v[126:127]
	v_pk_fma_f32 v[12:13], v[76:77], v[12:13], v[128:129]
	v_pk_fma_f32 v[14:15], v[78:79], v[14:15], v[130:131]
	v_pk_fma_f32 v[16:17], v[64:65], v[16:17], v[116:117]
	v_pk_fma_f32 v[18:19], v[66:67], v[18:19], v[118:119]
	v_pk_fma_f32 v[20:21], v[68:69], v[20:21], v[120:121]
	v_pk_fma_f32 v[22:23], v[70:71], v[22:23], v[122:123]
	v_pk_fma_f32 v[24:25], v[72:73], v[24:25], v[124:125]
	v_pk_fma_f32 v[26:27], v[74:75], v[26:27], v[126:127]
	v_pk_fma_f32 v[28:29], v[76:77], v[28:29], v[128:129]
	v_pk_fma_f32 v[30:31], v[78:79], v[30:31], v[130:131]
	v_pk_fma_f32 v[32:33], v[64:65], v[32:33], v[116:117]
	v_pk_fma_f32 v[34:35], v[66:67], v[34:35], v[118:119]
	v_pk_fma_f32 v[36:37], v[68:69], v[36:37], v[120:121]
	v_pk_fma_f32 v[38:39], v[70:71], v[38:39], v[122:123]
	v_pk_fma_f32 v[40:41], v[72:73], v[40:41], v[124:125]
	v_pk_fma_f32 v[42:43], v[74:75], v[42:43], v[126:127]
	v_pk_fma_f32 v[44:45], v[76:77], v[44:45], v[128:129]
	v_pk_fma_f32 v[46:47], v[78:79], v[46:47], v[130:131]
	v_pk_fma_f32 v[48:49], v[64:65], v[48:49], v[116:117]
	v_pk_fma_f32 v[50:51], v[66:67], v[50:51], v[118:119]
	v_pk_fma_f32 v[52:53], v[68:69], v[52:53], v[120:121]
	v_pk_fma_f32 v[54:55], v[70:71], v[54:55], v[122:123]
	v_pk_fma_f32 v[56:57], v[72:73], v[56:57], v[124:125]
	v_pk_fma_f32 v[58:59], v[74:75], v[58:59], v[126:127]
	v_pk_fma_f32 v[60:61], v[76:77], v[60:61], v[128:129]
	v_pk_fma_f32 v[62:63], v[78:79], v[62:63], v[130:131]
	v_cvt_pk_bf16_f32 v0, v0, v1
	v_cvt_pk_bf16_f32 v1, v2, v3
	v_cvt_pk_bf16_f32 v4, v4, v5
	v_cvt_pk_bf16_f32 v5, v6, v7
	v_cvt_pk_bf16_f32 v8, v8, v9
	v_cvt_pk_bf16_f32 v9, v10, v11
	v_cvt_pk_bf16_f32 v12, v12, v13
	v_cvt_pk_bf16_f32 v13, v14, v15
	v_cvt_pk_bf16_f32 v16, v16, v17
	v_cvt_pk_bf16_f32 v17, v18, v19
	v_cvt_pk_bf16_f32 v20, v20, v21
	v_cvt_pk_bf16_f32 v21, v22, v23
	v_cvt_pk_bf16_f32 v24, v24, v25
	v_cvt_pk_bf16_f32 v25, v26, v27
	v_cvt_pk_bf16_f32 v28, v28, v29
	v_cvt_pk_bf16_f32 v29, v30, v31
	v_cvt_pk_bf16_f32 v32, v32, v33
	v_cvt_pk_bf16_f32 v33, v34, v35
	v_cvt_pk_bf16_f32 v36, v36, v37
	v_cvt_pk_bf16_f32 v37, v38, v39
	v_cvt_pk_bf16_f32 v40, v40, v41
	v_cvt_pk_bf16_f32 v41, v42, v43
	v_cvt_pk_bf16_f32 v44, v44, v45
	v_cvt_pk_bf16_f32 v45, v46, v47
	v_cvt_pk_bf16_f32 v48, v48, v49
	v_cvt_pk_bf16_f32 v49, v50, v51
	v_cvt_pk_bf16_f32 v52, v52, v53
	v_cvt_pk_bf16_f32 v53, v54, v55
	v_cvt_pk_bf16_f32 v56, v56, v57
	v_cvt_pk_bf16_f32 v57, v58, v59
	v_cvt_pk_bf16_f32 v60, v60, v61
	v_cvt_pk_bf16_f32 v61, v62, v63
	global_store_dwordx2 v[230:231], v[0:1], off
	global_store_dwordx2 v[230:231], v[4:5], off offset:512
	global_store_dwordx2 v[230:231], v[8:9], off offset:1024
	global_store_dwordx2 v[230:231], v[12:13], off offset:1536
	global_store_dwordx2 v[230:231], v[16:17], off offset:2048
	global_store_dwordx2 v[230:231], v[20:21], off offset:2560
	global_store_dwordx2 v[230:231], v[24:25], off offset:3072
	global_store_dwordx2 v[230:231], v[28:29], off offset:3584
	global_store_dwordx2 v[232:233], v[32:33], off
	global_store_dwordx2 v[232:233], v[36:37], off offset:512
	global_store_dwordx2 v[232:233], v[40:41], off offset:1024
	global_store_dwordx2 v[232:233], v[44:45], off offset:1536
	global_store_dwordx2 v[232:233], v[48:49], off offset:2048
	global_store_dwordx2 v[232:233], v[52:53], off offset:2560
	global_store_dwordx2 v[232:233], v[56:57], off offset:3072
	global_store_dwordx2 v[232:233], v[60:61], off offset:3584
	s_waitcnt vmcnt(16)
	v_pk_mul_f32 v[220:221], v[136:137], v[136:137]
	v_pk_mul_f32 v[222:223], v[152:153], v[152:153]
	v_pk_mul_f32 v[224:225], v[168:169], v[168:169]
	v_pk_mul_f32 v[226:227], v[196:197], v[196:197]
	v_pk_fma_f32 v[220:221], v[138:139], v[138:139], v[220:221]
	v_pk_fma_f32 v[222:223], v[154:155], v[154:155], v[222:223]
	v_pk_fma_f32 v[224:225], v[170:171], v[170:171], v[224:225]
	v_pk_fma_f32 v[226:227], v[198:199], v[198:199], v[226:227]
	v_pk_fma_f32 v[220:221], v[140:141], v[140:141], v[220:221]
	v_pk_fma_f32 v[222:223], v[156:157], v[156:157], v[222:223]
	v_pk_fma_f32 v[224:225], v[184:185], v[184:185], v[224:225]
	v_pk_fma_f32 v[226:227], v[200:201], v[200:201], v[226:227]
	v_pk_fma_f32 v[220:221], v[142:143], v[142:143], v[220:221]
	v_pk_fma_f32 v[222:223], v[158:159], v[158:159], v[222:223]
	v_pk_fma_f32 v[224:225], v[186:187], v[186:187], v[224:225]
	v_pk_fma_f32 v[226:227], v[202:203], v[202:203], v[226:227]
	v_pk_fma_f32 v[220:221], v[144:145], v[144:145], v[220:221]
	v_pk_fma_f32 v[222:223], v[160:161], v[160:161], v[222:223]
	v_pk_fma_f32 v[224:225], v[188:189], v[188:189], v[224:225]
	v_pk_fma_f32 v[226:227], v[212:213], v[212:213], v[226:227]
	v_pk_fma_f32 v[220:221], v[146:147], v[146:147], v[220:221]
	v_pk_fma_f32 v[222:223], v[162:163], v[162:163], v[222:223]
	v_pk_fma_f32 v[224:225], v[190:191], v[190:191], v[224:225]
	v_pk_fma_f32 v[226:227], v[214:215], v[214:215], v[226:227]
	v_pk_fma_f32 v[220:221], v[148:149], v[148:149], v[220:221]
	v_pk_fma_f32 v[222:223], v[164:165], v[164:165], v[222:223]
	v_pk_fma_f32 v[224:225], v[192:193], v[192:193], v[224:225]
	v_pk_fma_f32 v[226:227], v[216:217], v[216:217], v[226:227]
	v_pk_fma_f32 v[220:221], v[150:151], v[150:151], v[220:221]
	v_pk_fma_f32 v[222:223], v[166:167], v[166:167], v[222:223]
	v_pk_fma_f32 v[224:225], v[194:195], v[194:195], v[224:225]
	v_pk_fma_f32 v[226:227], v[218:219], v[218:219], v[226:227]
	v_add_f32_e32 v220, v220, v221
	v_add_f32_e32 v222, v222, v223
	v_add_f32_e32 v224, v224, v225
	v_add_f32_e32 v226, v226, v227
	v_add_f32_dpp v220, v220, v220 quad_perm:[1,0,3,2] row_mask:0xf bank_mask:0xf
	v_add_f32_dpp v222, v222, v222 quad_perm:[1,0,3,2] row_mask:0xf bank_mask:0xf
	v_add_f32_dpp v224, v224, v224 quad_perm:[1,0,3,2] row_mask:0xf bank_mask:0xf
	v_add_f32_dpp v226, v226, v226 quad_perm:[1,0,3,2] row_mask:0xf bank_mask:0xf
	v_add_f32_dpp v220, v220, v220 quad_perm:[2,3,0,1] row_mask:0xf bank_mask:0xf
	v_add_f32_dpp v222, v222, v222 quad_perm:[2,3,0,1] row_mask:0xf bank_mask:0xf
	v_add_f32_dpp v224, v224, v224 quad_perm:[2,3,0,1] row_mask:0xf bank_mask:0xf
	v_add_f32_dpp v226, v226, v226 quad_perm:[2,3,0,1] row_mask:0xf bank_mask:0xf
	v_add_f32_dpp v220, v220, v220 row_half_mirror row_mask:0xf bank_mask:0xf
	v_add_f32_dpp v222, v222, v222 row_half_mirror row_mask:0xf bank_mask:0xf
	v_add_f32_dpp v224, v224, v224 row_half_mirror row_mask:0xf bank_mask:0xf
	v_add_f32_dpp v226, v226, v226 row_half_mirror row_mask:0xf bank_mask:0xf
	v_add_f32_dpp v220, v220, v220 row_mirror row_mask:0xf bank_mask:0xf
	v_add_f32_dpp v222, v222, v222 row_mirror row_mask:0xf bank_mask:0xf
	v_add_f32_dpp v224, v224, v224 row_mirror row_mask:0xf bank_mask:0xf
	v_add_f32_dpp v226, v226, v226 row_mirror row_mask:0xf bank_mask:0xf
	v_add_f32_dpp v220, v220, v220 row_bcast:15 row_mask:0xa bank_mask:0xf
	v_add_f32_dpp v222, v222, v222 row_bcast:15 row_mask:0xa bank_mask:0xf
	v_add_f32_dpp v224, v224, v224 row_bcast:15 row_mask:0xa bank_mask:0xf
	v_add_f32_dpp v226, v226, v226 row_bcast:15 row_mask:0xa bank_mask:0xf
	v_add_f32_dpp v220, v220, v220 row_bcast:31 row_mask:0xc bank_mask:0xf
	v_add_f32_dpp v222, v222, v222 row_bcast:31 row_mask:0xc bank_mask:0xf
	v_add_f32_dpp v224, v224, v224 row_bcast:31 row_mask:0xc bank_mask:0xf
	v_add_f32_dpp v226, v226, v226 row_bcast:31 row_mask:0xc bank_mask:0xf
	v_fma_f32 v220, v220, s88, v228
	v_fma_f32 v222, v222, s88, v228
	v_fma_f32 v224, v224, s88, v228
	v_fma_f32 v226, v226, s88, v228
	v_rsq_f32_e32 v220, v220
	v_rsq_f32_e32 v222, v222
	v_rsq_f32_e32 v224, v224
	v_rsq_f32_e32 v226, v226
	v_readlane_b32 s16, v220, 63
	v_readlane_b32 s17, v222, 63
	v_readlane_b32 s18, v224, 63
	v_readlane_b32 s19, v226, 63
	v_lshl_add_u64 v[230:231], v[84:85], 0, s[20:21]
	s_add_u32 s20, s20, 0x1000
	s_addc_u32 s21, s21, 0
	v_lshl_add_u64 v[232:233], v[84:85], 0, s[20:21]
	s_add_u32 s20, s20, 0x1000
	s_addc_u32 s21, s21, 0
	v_pk_mul_f32 v[136:137], v[136:137], s[16:17] op_sel_hi:[1,0]
	v_pk_mul_f32 v[138:139], v[138:139], s[16:17] op_sel_hi:[1,0]
	v_pk_mul_f32 v[140:141], v[140:141], s[16:17] op_sel_hi:[1,0]
	v_pk_mul_f32 v[142:143], v[142:143], s[16:17] op_sel_hi:[1,0]
	v_pk_mul_f32 v[144:145], v[144:145], s[16:17] op_sel_hi:[1,0]
	v_pk_mul_f32 v[146:147], v[146:147], s[16:17] op_sel_hi:[1,0]
	v_pk_mul_f32 v[148:149], v[148:149], s[16:17] op_sel_hi:[1,0]
	v_pk_mul_f32 v[150:151], v[150:151], s[16:17] op_sel_hi:[1,0]
	v_pk_mul_f32 v[152:153], v[152:153], s[16:17] op_sel:[0,1] op_sel_hi:[1,1]
	v_pk_mul_f32 v[154:155], v[154:155], s[16:17] op_sel:[0,1] op_sel_hi:[1,1]
	v_pk_mul_f32 v[156:157], v[156:157], s[16:17] op_sel:[0,1] op_sel_hi:[1,1]
	v_pk_mul_f32 v[158:159], v[158:159], s[16:17] op_sel:[0,1] op_sel_hi:[1,1]
	v_pk_mul_f32 v[160:161], v[160:161], s[16:17] op_sel:[0,1] op_sel_hi:[1,1]
	v_pk_mul_f32 v[162:163], v[162:163], s[16:17] op_sel:[0,1] op_sel_hi:[1,1]
	v_pk_mul_f32 v[164:165], v[164:165], s[16:17] op_sel:[0,1] op_sel_hi:[1,1]
	v_pk_mul_f32 v[166:167], v[166:167], s[16:17] op_sel:[0,1] op_sel_hi:[1,1]
	v_pk_mul_f32 v[168:169], v[168:169], s[18:19] op_sel_hi:[1,0]
	v_pk_mul_f32 v[170:171], v[170:171], s[18:19] op_sel_hi:[1,0]
	v_pk_mul_f32 v[184:185], v[184:185], s[18:19] op_sel_hi:[1,0]
	v_pk_mul_f32 v[186:187], v[186:187], s[18:19] op_sel_hi:[1,0]
	v_pk_mul_f32 v[188:189], v[188:189], s[18:19] op_sel_hi:[1,0]
	v_pk_mul_f32 v[190:191], v[190:191], s[18:19] op_sel_hi:[1,0]
	v_pk_mul_f32 v[192:193], v[192:193], s[18:19] op_sel_hi:[1,0]
	v_pk_mul_f32 v[194:195], v[194:195], s[18:19] op_sel_hi:[1,0]
	v_pk_mul_f32 v[196:197], v[196:197], s[18:19] op_sel:[0,1] op_sel_hi:[1,1]
	v_pk_mul_f32 v[198:199], v[198:199], s[18:19] op_sel:[0,1] op_sel_hi:[1,1]
	v_pk_mul_f32 v[200:201], v[200:201], s[18:19] op_sel:[0,1] op_sel_hi:[1,1]
	v_pk_mul_f32 v[202:203], v[202:203], s[18:19] op_sel:[0,1] op_sel_hi:[1,1]
	v_pk_mul_f32 v[212:213], v[212:213], s[18:19] op_sel:[0,1] op_sel_hi:[1,1]
	v_pk_mul_f32 v[214:215], v[214:215], s[18:19] op_sel:[0,1] op_sel_hi:[1,1]
	v_pk_mul_f32 v[216:217], v[216:217], s[18:19] op_sel:[0,1] op_sel_hi:[1,1]
	v_pk_mul_f32 v[218:219], v[218:219], s[18:19] op_sel:[0,1] op_sel_hi:[1,1]
	v_pk_fma_f32 v[136:137], v[64:65], v[136:137], v[116:117]
	v_pk_fma_f32 v[138:139], v[66:67], v[138:139], v[118:119]
	v_pk_fma_f32 v[140:141], v[68:69], v[140:141], v[120:121]
	v_pk_fma_f32 v[142:143], v[70:71], v[142:143], v[122:123]
	v_pk_fma_f32 v[144:145], v[72:73], v[144:145], v[124:125]
	v_pk_fma_f32 v[146:147], v[74:75], v[146:147], v[126:127]
	v_pk_fma_f32 v[148:149], v[76:77], v[148:149], v[128:129]
	v_pk_fma_f32 v[150:151], v[78:79], v[150:151], v[130:131]
	v_pk_fma_f32 v[152:153], v[64:65], v[152:153], v[116:117]
	v_pk_fma_f32 v[154:155], v[66:67], v[154:155], v[118:119]
	v_pk_fma_f32 v[156:157], v[68:69], v[156:157], v[120:121]
	v_pk_fma_f32 v[158:159], v[70:71], v[158:159], v[122:123]
	v_pk_fma_f32 v[160:161], v[72:73], v[160:161], v[124:125]
	v_pk_fma_f32 v[162:163], v[74:75], v[162:163], v[126:127]
	v_pk_fma_f32 v[164:165], v[76:77], v[164:165], v[128:129]
	v_pk_fma_f32 v[166:167], v[78:79], v[166:167], v[130:131]
	v_pk_fma_f32 v[168:169], v[64:65], v[168:169], v[116:117]
	v_pk_fma_f32 v[170:171], v[66:67], v[170:171], v[118:119]
	v_pk_fma_f32 v[184:185], v[68:69], v[184:185], v[120:121]
	v_pk_fma_f32 v[186:187], v[70:71], v[186:187], v[122:123]
	v_pk_fma_f32 v[188:189], v[72:73], v[188:189], v[124:125]
	v_pk_fma_f32 v[190:191], v[74:75], v[190:191], v[126:127]
	v_pk_fma_f32 v[192:193], v[76:77], v[192:193], v[128:129]
	v_pk_fma_f32 v[194:195], v[78:79], v[194:195], v[130:131]
	v_pk_fma_f32 v[196:197], v[64:65], v[196:197], v[116:117]
	v_pk_fma_f32 v[198:199], v[66:67], v[198:199], v[118:119]
	v_pk_fma_f32 v[200:201], v[68:69], v[200:201], v[120:121]
	v_pk_fma_f32 v[202:203], v[70:71], v[202:203], v[122:123]
	v_pk_fma_f32 v[212:213], v[72:73], v[212:213], v[124:125]
	v_pk_fma_f32 v[214:215], v[74:75], v[214:215], v[126:127]
	v_pk_fma_f32 v[216:217], v[76:77], v[216:217], v[128:129]
	v_pk_fma_f32 v[218:219], v[78:79], v[218:219], v[130:131]
	v_cvt_pk_bf16_f32 v136, v136, v137
	v_cvt_pk_bf16_f32 v137, v138, v139
	v_cvt_pk_bf16_f32 v140, v140, v141
	v_cvt_pk_bf16_f32 v141, v142, v143
	v_cvt_pk_bf16_f32 v144, v144, v145
	v_cvt_pk_bf16_f32 v145, v146, v147
	v_cvt_pk_bf16_f32 v148, v148, v149
	v_cvt_pk_bf16_f32 v149, v150, v151
	v_cvt_pk_bf16_f32 v152, v152, v153
	v_cvt_pk_bf16_f32 v153, v154, v155
	v_cvt_pk_bf16_f32 v156, v156, v157
	v_cvt_pk_bf16_f32 v157, v158, v159
	v_cvt_pk_bf16_f32 v160, v160, v161
	v_cvt_pk_bf16_f32 v161, v162, v163
	v_cvt_pk_bf16_f32 v164, v164, v165
	v_cvt_pk_bf16_f32 v165, v166, v167
	v_cvt_pk_bf16_f32 v168, v168, v169
	v_cvt_pk_bf16_f32 v169, v170, v171
	v_cvt_pk_bf16_f32 v184, v184, v185
	v_cvt_pk_bf16_f32 v185, v186, v187
	v_cvt_pk_bf16_f32 v188, v188, v189
	v_cvt_pk_bf16_f32 v189, v190, v191
	v_cvt_pk_bf16_f32 v192, v192, v193
	v_cvt_pk_bf16_f32 v193, v194, v195
	v_cvt_pk_bf16_f32 v196, v196, v197
	v_cvt_pk_bf16_f32 v197, v198, v199
	v_cvt_pk_bf16_f32 v200, v200, v201
	v_cvt_pk_bf16_f32 v201, v202, v203
	v_cvt_pk_bf16_f32 v212, v212, v213
	v_cvt_pk_bf16_f32 v213, v214, v215
	v_cvt_pk_bf16_f32 v216, v216, v217
	v_cvt_pk_bf16_f32 v217, v218, v219
	global_store_dwordx2 v[230:231], v[136:137], off
	global_store_dwordx2 v[230:231], v[140:141], off offset:512
	global_store_dwordx2 v[230:231], v[144:145], off offset:1024
	global_store_dwordx2 v[230:231], v[148:149], off offset:1536
	global_store_dwordx2 v[230:231], v[152:153], off offset:2048
	global_store_dwordx2 v[230:231], v[156:157], off offset:2560
	global_store_dwordx2 v[230:231], v[160:161], off offset:3072
	global_store_dwordx2 v[230:231], v[164:165], off offset:3584
	global_store_dwordx2 v[232:233], v[168:169], off
	global_store_dwordx2 v[232:233], v[184:185], off offset:512
	global_store_dwordx2 v[232:233], v[188:189], off offset:1024
	global_store_dwordx2 v[232:233], v[192:193], off offset:1536
	global_store_dwordx2 v[232:233], v[196:197], off offset:2048
	global_store_dwordx2 v[232:233], v[200:201], off offset:2560
	global_store_dwordx2 v[232:233], v[212:213], off offset:3072
	global_store_dwordx2 v[232:233], v[216:217], off offset:3584
	s_mov_b32 s22, 0x8000
	s_mov_b32 s23, 0
	s_add_i32 s24, s24, s58
	s_add_i32 s6, s6, s27
	s_add_i32 s8, s8, s27
	s_add_i32 s10, s10, s27
	s_add_i32 s12, s12, s27
	s_cmpk_gt_i32 s24, 0x7ff
	s_cbranch_scc0 .LBB0_533
